# s_setprio 3 for Griffin items (critical chain of phase 7), reset to 0 on leaving the Griffin loop
# speedup vs baseline: 1.0043x; 1.0043x over previous
.LBB0_476:
	s_or_b64 exec, exec, s[14:15]
	s_waitcnt lgkmcnt(0)
	s_barrier
	ds_read_b32 v2, v242
	s_mov_b64 s[14:15], -1
	s_waitcnt lgkmcnt(0)
	v_cmp_lt_i32_e32 vcc, s36, v2
	v_readfirstlane_b32 s23, v2
	s_cbranch_vccnz .LBB0_471
	s_setprio 3
	s_load_dwordx16 s[60:75], s[0:1], 0x40
	s_bfe_u32 s27, s23, 0x30002
	s_lshl_b32 s24, s27, 6
	v_or_b32_e32 v148, s24, v229
	s_waitcnt lgkmcnt(0)
	v_lshl_add_u64 v[2:3], v[148:149], 2, s[68:69]
	s_barrier
	global_load_dword v2, v[2:3], off
	v_readfirstlane_b32 s25, v226
	s_waitcnt vmcnt(0)
	ds_write_b32 v230, v2 offset:8320
	s_and_saveexec_b64 s[14:15], s[4:5]
	s_cbranch_execz .LBB0_479
	s_load_dwordx16 s[60:75], s[0:1], 0x40
	v_or_b32_e32 v148, s24, v1
	s_waitcnt lgkmcnt(0)
	v_lshl_add_u64 v[2:3], v[148:149], 2, s[70:71]
	global_load_dword v2, v[2:3], off
	s_waitcnt vmcnt(0)
	ds_write_b32 v230, v2 offset:9344

.LBB0_529:
	s_setprio 0
	s_mov_b64 s[28:29], s[76:77]
	s_mov_b32 s30, s78
